# v98 + P4->P5 grid barrier split: arrive (release) after the combine, wait (acquire) at the end of the merge GEMM's first segment boundary
# baseline (speedup 1.0000x reference)
.LBB0_725:
	s_or_b64 exec, exec, s[0:1]
	v_readlane_b32 s2, v253, 1
	v_readlane_b32 s3, v253, 2
	s_waitcnt vmcnt(0)
	s_barrier
	s_mov_b64 s[0:1], exec
	v_readlane_b32 s4, v253, 5
	v_readlane_b32 s5, v253, 6
	s_and_b64 s[4:5], s[0:1], s[4:5]
	s_mov_b64 exec, s[4:5]
	s_cbranch_execz .LBB0_777
	s_load_dwordx2 s[4:5], s[2:3], 0xd8
	v_readlane_b32 s2, v255, 17
	v_readlane_b32 s3, v255, 18
	s_waitcnt vmcnt(0) expcnt(0) lgkmcnt(0)
	v_mov_b32_e32 v0, s2
	ds_read_b32 v2, v0
	v_mov_b32_e32 v0, s3
	ds_read_b32 v3, v0
	s_add_u32 s8, s4, 0x3500
	s_addc_u32 s9, s5, 0
	global_load_dword v4, v1, s[8:9] sc1
	v_readlane_b32 s6, v253, 61
	s_lshl_b32 s6, s6, 2
	s_add_u32 s6, s4, s6
	s_addc_u32 s7, s5, 0
	v_mov_b32_e32 v5, 1
	s_waitcnt vmcnt(0) lgkmcnt(0)
	v_readfirstlane_b32 s10, v4
	s_nop 0
	v_writelane_b32 v255, s10, 53
	global_atomic_add v6, v252, v5, s[6:7] offset:1024 sc0
	v_add_u32_e32 v7, 1, v4
	v_mul_lo_u32 v8, v7, v2
	s_waitcnt vmcnt(0)
	v_add_u32_e32 v6, 1, v6
	v_cmp_eq_u32_e32 vcc, v6, v8
	s_cbranch_vccz .Lsa_done
	buffer_wbl2 sc1
	s_waitcnt vmcnt(0)
	global_atomic_add v6, v205, v5, s[4:5] offset:1024 sc0
	v_mul_lo_u32 v8, v7, v3
	s_waitcnt vmcnt(0)
	v_add_u32_e32 v6, 1, v6
	v_cmp_eq_u32_e32 vcc, v6, v8
	s_cbranch_vccz .Lsa_xgen
	global_atomic_add v1, v5, s[8:9]
.Lsa_xgen:
	global_atomic_add v204, v5, s[6:7] offset:1024
	s_waitcnt vmcnt(0)
.Lsa_done:
.LBB0_777:
	s_or_b64 exec, exec, s[0:1]
	v_readlane_b32 s0, v253, 1
	v_readlane_b32 s2, v255, 50
	v_readlane_b32 s1, v253, 2
	v_readlane_b32 s3, v255, 51
	s_waitcnt lgkmcnt(0)
	s_barrier
	v_mbcnt_lo_u32_b32 v16, -1, 0
	v_mbcnt_hi_u32_b32 v16, -1, v16
	s_and_b64 vcc, exec, s[2:3]
	s_cbranch_vccnz .LBB0_801
	v_lshl_add_u32 v0, v16, 4, s33
	v_add_u32_e32 v2, 0x2000, v0
	v_ashrrev_i32_e32 v3, 31, v2
	v_lshrrev_b32_e32 v3, 22, v3
	v_add_u32_e32 v3, v2, v3
	v_ashrrev_i32_e32 v10, 10, v3
	v_mul_i32_i24_e32 v3, 0x400, v10
	v_sub_u32_e32 v2, v2, v3
	v_lshrrev_b32_e32 v3, 4, v2
	v_bitop3_b32 v2, v3, v2, 32 bitop3:0x6c
	v_ashrrev_i32_e32 v3, 31, v2
	v_lshrrev_b32_e32 v3, 26, v3
	v_add_u32_e32 v3, v2, v3
	v_ashrrev_i32_e32 v11, 6, v3
	v_lshlrev_b32_e32 v4, 3, v10
	v_and_b32_e32 v3, 0xffc0, v3
	v_and_b32_e32 v4, -16, v4
	v_sub_u32_e32 v2, v2, v3
	v_add_u32_e32 v4, v11, v4
	v_lshrrev_b16_e32 v3, 7, v2
	s_load_dwordx2 s[6:7], s[0:1], 0xd8
	v_and_b32_e32 v5, 3, v11
	s_mov_b32 s0, 0x3fffe0
	v_lshrrev_b32_e32 v6, 2, v4
	v_lshlrev_b32_e32 v7, 1, v4
	v_and_b32_e32 v3, 1, v3
	v_and_or_b32 v5, v4, s0, v5
	v_and_b32_e32 v6, 4, v6
	v_and_b32_e32 v7, 24, v7
	v_add_u16_e32 v2, v2, v3
	v_or3_b32 v5, v5, v6, v7
	v_lshlrev_b32_e32 v6, 5, v10
	v_ashrrev_i16_sdwa v2, v206, sext(v2) dst_sel:DWORD dst_unused:UNUSED_PAD src0_sel:DWORD src1_sel:BYTE_0
	v_and_b32_e32 v6, 32, v6
	v_bfe_i32 v12, v2, 0, 16
	v_add_lshl_u32 v2, v6, v12, 1
	v_lshl_add_u32 v154, v5, 10, v2
	v_lshl_add_u32 v156, v4, 10, v2
	v_ashrrev_i32_e32 v2, 31, v0
	v_lshrrev_b32_e32 v2, 22, v2
	v_add_u32_e32 v2, v0, v2
	v_ashrrev_i32_e32 v13, 10, v2
	v_mul_i32_i24_e32 v2, 0x400, v13
	v_sub_u32_e32 v0, v0, v2
	v_lshrrev_b32_e32 v2, 4, v0
	v_bitop3_b32 v0, v2, v0, 32 bitop3:0x6c
	v_ashrrev_i32_e32 v2, 31, v0
	v_lshrrev_b32_e32 v2, 26, v2
	v_add_u32_e32 v2, v0, v2
	v_lshlrev_b32_e32 v3, 3, v13
	v_ashrrev_i32_e32 v14, 6, v2
	v_and_b32_e32 v3, -16, v3
	s_waitcnt lgkmcnt(0)
	s_add_u32 s20, s6, 0x8600000
	v_add_u32_e32 v3, v14, v3
	s_addc_u32 s21, s7, 0
	v_and_b32_e32 v4, 3, v14
	v_lshrrev_b32_e32 v5, 2, v3
	v_lshlrev_b32_e32 v6, 1, v3
	v_and_b32_e32 v2, 0xc0, v2
	s_add_u32 s26, s6, 0x1a00000
	v_and_or_b32 v4, v3, s0, v4
	v_and_b32_e32 v5, 4, v5
	v_and_b32_e32 v6, 24, v6
	v_sub_u32_e32 v0, v0, v2
	s_addc_u32 s28, s7, 0
	v_or3_b32 v4, v4, v5, v6
	v_lshlrev_b32_e32 v5, 5, v13
	v_ashrrev_i16_sdwa v0, v206, sext(v0) dst_sel:DWORD dst_unused:UNUSED_PAD src0_sel:DWORD src1_sel:BYTE_0
	v_readlane_b32 s0, v254, 37
	v_and_b32_e32 v5, 32, v5
	v_bfe_i32 v15, v0, 0, 16
	v_readlane_b32 s1, v254, 38
	s_add_u32 s22, s26, s0
	v_add_lshl_u32 v2, v5, v15, 1
	s_addc_u32 s23, s28, s1
	s_add_i32 s29, s33, 0
	v_lshl_add_u32 v0, v4, 10, v2
	s_add_i32 m0, s29, 0x10000
	v_lshl_add_u32 v158, v3, 10, v2
	global_load_lds_dwordx4 v0, s[22:23]
	s_add_i32 m0, s29, 0x12000
	s_add_u32 s0, s22, 0x20000
	global_load_lds_dwordx4 v154, s[22:23]
	s_addc_u32 s1, s23, 0
	s_add_i32 m0, s29, 0x14000
	v_mov_b32_e32 v155, v1
	global_load_lds_dwordx4 v0, s[0:1]
	s_add_i32 m0, s29, 0x16000
	v_mov_b32_e32 v159, v1
	global_load_lds_dwordx4 v154, s[0:1]
	v_readlane_b32 s0, v254, 51
	v_readlane_b32 s1, v254, 52
	s_add_u32 s0, s20, s0
	s_addc_u32 s1, s21, s1
	s_add_i32 s30, s29, 0x2000
	s_mov_b32 m0, s29
	s_add_u32 s2, s0, 0x20000
	global_load_lds_dwordx4 v158, s[0:1]
	s_mov_b32 m0, s30
	s_addc_u32 s3, s1, 0
	s_add_i32 s31, s29, 0x4000
	global_load_lds_dwordx4 v156, s[0:1]
	s_mov_b32 m0, s31
	s_add_i32 s34, s29, 0x6000
	global_load_lds_dwordx4 v158, s[2:3]
	s_mov_b32 m0, s34
	v_mov_b32_e32 v157, v1
	global_load_lds_dwordx4 v156, s[2:3]
	v_readlane_b32 s2, v254, 4
	v_readlane_b32 s3, v254, 5
	v_lshl_add_u64 v[2:3], s[22:23], 0, v[0:1]
	v_lshl_add_u64 v[4:5], s[22:23], 0, v[154:155]
	v_cndmask_b32_e64 v17, 0, 1, s[2:3]
	v_lshl_add_u64 v[6:7], s[0:1], 0, v[158:159]
	v_lshl_add_u64 v[8:9], s[0:1], 0, v[156:157]
	v_cmp_ne_u32_e64 s[40:41], 1, v17
	s_andn2_b64 vcc, exec, s[2:3]
	s_cbranch_vccnz .LBB0_780
	s_barrier

.LBB0_793:
	s_lshl_b32 s2, s47, 8
	v_readlane_b32 s3, v253, 62
	s_add_i32 s2, s2, s3
	v_add_u32_e32 v250, s2, v194
	s_lshl_b32 s2, s46, 8
	v_readlane_b32 s3, v254, 18
	s_or_b32 s2, s2, s3
	v_lshl_add_u32 v251, v195, 3, s2
	v_lshlrev_b32_e32 v251, 1, v251
	v_lshl_add_u32 v248, v250, 13, v251
	v_lshl_add_u32 v249, v250, 11, v251
	s_lshl_b32 s0, s45, 11
	s_add_u32 s0, s4, s0
	s_addc_u32 s1, s5, 0
	s_mov_b64 s[56:57], s[0:1]
	s_mov_b64 s[82:83], s[6:7]
	s_add_u32 s58, s0, 0x20000
	s_addc_u32 s59, s1, 0
	s_add_u32 s84, s6, 0x8000
	s_addc_u32 s85, s7, 0
	s_add_u32 s60, s0, 0x40000
	s_addc_u32 s61, s1, 0
	s_add_u32 s86, s6, 0x10000
	s_addc_u32 s87, s7, 0
	s_add_u32 s62, s0, 0x60000
	s_addc_u32 s63, s1, 0
	s_add_u32 s88, s6, 0x18000
	s_addc_u32 s89, s7, 0
	s_add_u32 s64, s0, 0x100000
	s_addc_u32 s65, s1, 0
	s_add_u32 s90, s6, 0x40000
	s_addc_u32 s91, s7, 0
	s_add_u32 s66, s0, 0x120000
	s_addc_u32 s67, s1, 0
	s_add_u32 s92, s6, 0x48000
	s_addc_u32 s93, s7, 0
	s_add_u32 s68, s0, 0x140000
	s_addc_u32 s69, s1, 0
	s_add_u32 s94, s6, 0x50000
	s_addc_u32 s95, s7, 0
	s_add_u32 s70, s0, 0x160000
	s_addc_u32 s71, s1, 0
	s_add_u32 s96, s6, 0x58000
	s_addc_u32 s97, s7, 0
	s_cmp_eq_u32 s45, 3
	s_cbranch_scc1 .Lm_final
	global_load_dwordx4 v[130:133], v248, s[56:57]
	global_load_dwordx4 v[134:137], v248, s[56:57] offset:2048
	global_load_dwordx4 v[138:141], v248, s[56:57] offset:256
	global_load_dwordx4 v[142:145], v248, s[56:57] offset:2304
	global_load_dwordx4 v[146:149], v248, s[58:59]
	global_load_dwordx4 v[150:153], v248, s[58:59] offset:2048
	global_load_dwordx4 v[164:167], v248, s[58:59] offset:256
	global_load_dwordx4 v[168:171], v248, s[58:59] offset:2304
	global_load_dwordx4 v[172:175], v248, s[60:61]
	global_load_dwordx4 v[180:183], v248, s[60:61] offset:2048
	global_load_dwordx4 v[184:187], v248, s[60:61] offset:256
	global_load_dwordx4 v[188:191], v248, s[60:61] offset:2304
	global_load_dwordx4 v[198:201], v248, s[62:63]
	global_load_dwordx4 v[212:215], v248, s[62:63] offset:2048
	global_load_dwordx4 v[216:219], v248, s[62:63] offset:256
	global_load_dwordx4 v[220:223], v248, s[62:63] offset:2304
	global_load_dwordx4 v[224:227], v248, s[64:65]
	global_load_dwordx4 v[228:231], v248, s[64:65] offset:2048
	global_load_dwordx4 v[232:235], v248, s[64:65] offset:256
	global_load_dwordx4 v[236:239], v248, s[64:65] offset:2304
	global_load_dwordx4 v[240:243], v248, s[66:67]
	global_load_dwordx4 v[244:247], v248, s[66:67] offset:2048
	s_waitcnt vmcnt(20)
	v_lshlrev_b32_e32 v250, 16, v134
	v_and_b32_e32 v251, 0xffff0000, v134
	v_lshlrev_b32_e32 v192, 16, v130
	v_and_b32_e32 v193, 0xffff0000, v130
	v_max_f32_e32 v250, 0x0da24260, v250
	v_max_f32_e32 v251, 0x0da24260, v251
	v_rcp_f32_e32 v250, v250
	v_rcp_f32_e32 v251, v251
	v_max_f32_e32 v192, 0x0da24260, v192
	v_max_f32_e32 v193, 0x0da24260, v193
	v_mul_f32_e32 v250, v250, v192
	v_mul_f32_e32 v251, v251, v193
	v_mul_f32_e32 v126, v126, v250
	v_mul_f32_e32 v127, v127, v251
	v_lshlrev_b32_e32 v250, 16, v135
	v_and_b32_e32 v251, 0xffff0000, v135
	v_lshlrev_b32_e32 v192, 16, v131
	v_and_b32_e32 v193, 0xffff0000, v131
	v_max_f32_e32 v250, 0x0da24260, v250
	v_max_f32_e32 v251, 0x0da24260, v251
	v_rcp_f32_e32 v250, v250
	v_rcp_f32_e32 v251, v251
	v_max_f32_e32 v192, 0x0da24260, v192
	v_max_f32_e32 v193, 0x0da24260, v193
	v_mul_f32_e32 v250, v250, v192
	v_mul_f32_e32 v251, v251, v193
	v_mul_f32_e32 v128, v128, v250
	v_mul_f32_e32 v129, v129, v251
	v_lshlrev_b32_e32 v250, 16, v136
	v_and_b32_e32 v251, 0xffff0000, v136
	v_lshlrev_b32_e32 v192, 16, v132
	v_and_b32_e32 v193, 0xffff0000, v132
	v_max_f32_e32 v250, 0x0da24260, v250
	v_max_f32_e32 v251, 0x0da24260, v251
	v_rcp_f32_e32 v250, v250
	v_rcp_f32_e32 v251, v251
	v_max_f32_e32 v192, 0x0da24260, v192
	v_max_f32_e32 v193, 0x0da24260, v193
	v_mul_f32_e32 v250, v250, v192
	v_mul_f32_e32 v251, v251, v193
	v_mul_f32_e32 v122, v122, v250
	v_mul_f32_e32 v123, v123, v251
	v_lshlrev_b32_e32 v250, 16, v137
	v_and_b32_e32 v251, 0xffff0000, v137
	v_lshlrev_b32_e32 v192, 16, v133
	v_and_b32_e32 v193, 0xffff0000, v133
	v_max_f32_e32 v250, 0x0da24260, v250
	v_max_f32_e32 v251, 0x0da24260, v251
	v_rcp_f32_e32 v250, v250
	v_rcp_f32_e32 v251, v251
	v_max_f32_e32 v192, 0x0da24260, v192
	v_max_f32_e32 v193, 0x0da24260, v193
	v_mul_f32_e32 v250, v250, v192
	v_mul_f32_e32 v251, v251, v193
	v_mul_f32_e32 v124, v124, v250
	v_mul_f32_e32 v125, v125, v251
	global_load_dwordx4 v[130:133], v248, s[66:67] offset:256
	global_load_dwordx4 v[134:137], v248, s[66:67] offset:2304
	s_waitcnt vmcnt(20)
	v_lshlrev_b32_e32 v250, 16, v142
	v_and_b32_e32 v251, 0xffff0000, v142
	v_lshlrev_b32_e32 v192, 16, v138
	v_and_b32_e32 v193, 0xffff0000, v138
	v_max_f32_e32 v250, 0x0da24260, v250
	v_max_f32_e32 v251, 0x0da24260, v251
	v_rcp_f32_e32 v250, v250
	v_rcp_f32_e32 v251, v251
	v_max_f32_e32 v192, 0x0da24260, v192
	v_max_f32_e32 v193, 0x0da24260, v193
	v_mul_f32_e32 v250, v250, v192
	v_mul_f32_e32 v251, v251, v193
	v_mul_f32_e32 v114, v114, v250
	v_mul_f32_e32 v115, v115, v251
	v_lshlrev_b32_e32 v250, 16, v143
	v_and_b32_e32 v251, 0xffff0000, v143
	v_lshlrev_b32_e32 v192, 16, v139
	v_and_b32_e32 v193, 0xffff0000, v139
	v_max_f32_e32 v250, 0x0da24260, v250
	v_max_f32_e32 v251, 0x0da24260, v251
	v_rcp_f32_e32 v250, v250
	v_rcp_f32_e32 v251, v251
	v_max_f32_e32 v192, 0x0da24260, v192
	v_max_f32_e32 v193, 0x0da24260, v193
	v_mul_f32_e32 v250, v250, v192
	v_mul_f32_e32 v251, v251, v193
	v_mul_f32_e32 v116, v116, v250
	v_mul_f32_e32 v117, v117, v251
	v_lshlrev_b32_e32 v250, 16, v144
	v_and_b32_e32 v251, 0xffff0000, v144
	v_lshlrev_b32_e32 v192, 16, v140
	v_and_b32_e32 v193, 0xffff0000, v140
	v_max_f32_e32 v250, 0x0da24260, v250
	v_max_f32_e32 v251, 0x0da24260, v251
	v_rcp_f32_e32 v250, v250
	v_rcp_f32_e32 v251, v251
	v_max_f32_e32 v192, 0x0da24260, v192
	v_max_f32_e32 v193, 0x0da24260, v193
	v_mul_f32_e32 v250, v250, v192
	v_mul_f32_e32 v251, v251, v193
	v_mul_f32_e32 v106, v106, v250
	v_mul_f32_e32 v107, v107, v251
	v_lshlrev_b32_e32 v250, 16, v145
	v_and_b32_e32 v251, 0xffff0000, v145
	v_lshlrev_b32_e32 v192, 16, v141
	v_and_b32_e32 v193, 0xffff0000, v141
	v_max_f32_e32 v250, 0x0da24260, v250
	v_max_f32_e32 v251, 0x0da24260, v251
	v_rcp_f32_e32 v250, v250
	v_rcp_f32_e32 v251, v251
	v_max_f32_e32 v192, 0x0da24260, v192
	v_max_f32_e32 v193, 0x0da24260, v193
	v_mul_f32_e32 v250, v250, v192
	v_mul_f32_e32 v251, v251, v193
	v_mul_f32_e32 v108, v108, v250
	v_mul_f32_e32 v109, v109, v251
	global_load_dwordx4 v[138:141], v248, s[68:69]
	global_load_dwordx4 v[142:145], v248, s[68:69] offset:2048
	s_waitcnt vmcnt(20)
	v_lshlrev_b32_e32 v250, 16, v150
	v_and_b32_e32 v251, 0xffff0000, v150
	v_lshlrev_b32_e32 v192, 16, v146
	v_and_b32_e32 v193, 0xffff0000, v146
	v_max_f32_e32 v250, 0x0da24260, v250
	v_max_f32_e32 v251, 0x0da24260, v251
	v_rcp_f32_e32 v250, v250
	v_rcp_f32_e32 v251, v251
	v_max_f32_e32 v192, 0x0da24260, v192
	v_max_f32_e32 v193, 0x0da24260, v193
	v_mul_f32_e32 v250, v250, v192
	v_mul_f32_e32 v251, v251, v193
	v_mul_f32_e32 v118, v118, v250
	v_mul_f32_e32 v119, v119, v251
	v_lshlrev_b32_e32 v250, 16, v151
	v_and_b32_e32 v251, 0xffff0000, v151
	v_lshlrev_b32_e32 v192, 16, v147
	v_and_b32_e32 v193, 0xffff0000, v147
	v_max_f32_e32 v250, 0x0da24260, v250
	v_max_f32_e32 v251, 0x0da24260, v251
	v_rcp_f32_e32 v250, v250
	v_rcp_f32_e32 v251, v251
	v_max_f32_e32 v192, 0x0da24260, v192
	v_max_f32_e32 v193, 0x0da24260, v193
	v_mul_f32_e32 v250, v250, v192
	v_mul_f32_e32 v251, v251, v193
	v_mul_f32_e32 v120, v120, v250
	v_mul_f32_e32 v121, v121, v251
	v_lshlrev_b32_e32 v250, 16, v152
	v_and_b32_e32 v251, 0xffff0000, v152
	v_lshlrev_b32_e32 v192, 16, v148
	v_and_b32_e32 v193, 0xffff0000, v148
	v_max_f32_e32 v250, 0x0da24260, v250
	v_max_f32_e32 v251, 0x0da24260, v251
	v_rcp_f32_e32 v250, v250
	v_rcp_f32_e32 v251, v251
	v_max_f32_e32 v192, 0x0da24260, v192
	v_max_f32_e32 v193, 0x0da24260, v193
	v_mul_f32_e32 v250, v250, v192
	v_mul_f32_e32 v251, v251, v193
	v_mul_f32_e32 v110, v110, v250
	v_mul_f32_e32 v111, v111, v251
	v_lshlrev_b32_e32 v250, 16, v153
	v_and_b32_e32 v251, 0xffff0000, v153
	v_lshlrev_b32_e32 v192, 16, v149
	v_and_b32_e32 v193, 0xffff0000, v149
	v_max_f32_e32 v250, 0x0da24260, v250
	v_max_f32_e32 v251, 0x0da24260, v251
	v_rcp_f32_e32 v250, v250
	v_rcp_f32_e32 v251, v251
	v_max_f32_e32 v192, 0x0da24260, v192
	v_max_f32_e32 v193, 0x0da24260, v193
	v_mul_f32_e32 v250, v250, v192
	v_mul_f32_e32 v251, v251, v193
	v_mul_f32_e32 v112, v112, v250
	v_mul_f32_e32 v113, v113, v251
	global_load_dwordx4 v[146:149], v248, s[68:69] offset:256
	global_load_dwordx4 v[150:153], v248, s[68:69] offset:2304
	s_waitcnt vmcnt(20)
	v_lshlrev_b32_e32 v250, 16, v168
	v_and_b32_e32 v251, 0xffff0000, v168
	v_lshlrev_b32_e32 v192, 16, v164
	v_and_b32_e32 v193, 0xffff0000, v164
	v_max_f32_e32 v250, 0x0da24260, v250
	v_max_f32_e32 v251, 0x0da24260, v251
	v_rcp_f32_e32 v250, v250
	v_rcp_f32_e32 v251, v251
	v_max_f32_e32 v192, 0x0da24260, v192
	v_max_f32_e32 v193, 0x0da24260, v193
	v_mul_f32_e32 v250, v250, v192
	v_mul_f32_e32 v251, v251, v193
	v_mul_f32_e32 v102, v102, v250
	v_mul_f32_e32 v103, v103, v251
	v_lshlrev_b32_e32 v250, 16, v169
	v_and_b32_e32 v251, 0xffff0000, v169
	v_lshlrev_b32_e32 v192, 16, v165
	v_and_b32_e32 v193, 0xffff0000, v165
	v_max_f32_e32 v250, 0x0da24260, v250
	v_max_f32_e32 v251, 0x0da24260, v251
	v_rcp_f32_e32 v250, v250
	v_rcp_f32_e32 v251, v251
	v_max_f32_e32 v192, 0x0da24260, v192
	v_max_f32_e32 v193, 0x0da24260, v193
	v_mul_f32_e32 v250, v250, v192
	v_mul_f32_e32 v251, v251, v193
	v_mul_f32_e32 v104, v104, v250
	v_mul_f32_e32 v105, v105, v251
	v_lshlrev_b32_e32 v250, 16, v170
	v_and_b32_e32 v251, 0xffff0000, v170
	v_lshlrev_b32_e32 v192, 16, v166
	v_and_b32_e32 v193, 0xffff0000, v166
	v_max_f32_e32 v250, 0x0da24260, v250
	v_max_f32_e32 v251, 0x0da24260, v251
	v_rcp_f32_e32 v250, v250
	v_rcp_f32_e32 v251, v251
	v_max_f32_e32 v192, 0x0da24260, v192
	v_max_f32_e32 v193, 0x0da24260, v193
	v_mul_f32_e32 v250, v250, v192
	v_mul_f32_e32 v251, v251, v193
	v_mul_f32_e32 v98, v98, v250
	v_mul_f32_e32 v99, v99, v251
	v_lshlrev_b32_e32 v250, 16, v171
	v_and_b32_e32 v251, 0xffff0000, v171
	v_lshlrev_b32_e32 v192, 16, v167
	v_and_b32_e32 v193, 0xffff0000, v167
	v_max_f32_e32 v250, 0x0da24260, v250
	v_max_f32_e32 v251, 0x0da24260, v251
	v_rcp_f32_e32 v250, v250
	v_rcp_f32_e32 v251, v251
	v_max_f32_e32 v192, 0x0da24260, v192
	v_max_f32_e32 v193, 0x0da24260, v193
	v_mul_f32_e32 v250, v250, v192
	v_mul_f32_e32 v251, v251, v193
	v_mul_f32_e32 v100, v100, v250
	v_mul_f32_e32 v101, v101, v251
	global_load_dwordx4 v[164:167], v248, s[70:71]
	global_load_dwordx4 v[168:171], v248, s[70:71] offset:2048
	s_waitcnt vmcnt(20)
	v_lshlrev_b32_e32 v250, 16, v180
	v_and_b32_e32 v251, 0xffff0000, v180
	v_lshlrev_b32_e32 v192, 16, v172
	v_and_b32_e32 v193, 0xffff0000, v172
	v_max_f32_e32 v250, 0x0da24260, v250
	v_max_f32_e32 v251, 0x0da24260, v251
	v_rcp_f32_e32 v250, v250
	v_rcp_f32_e32 v251, v251
	v_max_f32_e32 v192, 0x0da24260, v192
	v_max_f32_e32 v193, 0x0da24260, v193
	v_mul_f32_e32 v250, v250, v192
	v_mul_f32_e32 v251, v251, v193
	v_mul_f32_e32 v94, v94, v250
	v_mul_f32_e32 v95, v95, v251
	v_lshlrev_b32_e32 v250, 16, v181
	v_and_b32_e32 v251, 0xffff0000, v181
	v_lshlrev_b32_e32 v192, 16, v173
	v_and_b32_e32 v193, 0xffff0000, v173
	v_max_f32_e32 v250, 0x0da24260, v250
	v_max_f32_e32 v251, 0x0da24260, v251
	v_rcp_f32_e32 v250, v250
	v_rcp_f32_e32 v251, v251
	v_max_f32_e32 v192, 0x0da24260, v192
	v_max_f32_e32 v193, 0x0da24260, v193
	v_mul_f32_e32 v250, v250, v192
	v_mul_f32_e32 v251, v251, v193
	v_mul_f32_e32 v96, v96, v250
	v_mul_f32_e32 v97, v97, v251
	v_lshlrev_b32_e32 v250, 16, v182
	v_and_b32_e32 v251, 0xffff0000, v182
	v_lshlrev_b32_e32 v192, 16, v174
	v_and_b32_e32 v193, 0xffff0000, v174
	v_max_f32_e32 v250, 0x0da24260, v250
	v_max_f32_e32 v251, 0x0da24260, v251
	v_rcp_f32_e32 v250, v250
	v_rcp_f32_e32 v251, v251
	v_max_f32_e32 v192, 0x0da24260, v192
	v_max_f32_e32 v193, 0x0da24260, v193
	v_mul_f32_e32 v250, v250, v192
	v_mul_f32_e32 v251, v251, v193
	v_mul_f32_e32 v90, v90, v250
	v_mul_f32_e32 v91, v91, v251
	v_lshlrev_b32_e32 v250, 16, v183
	v_and_b32_e32 v251, 0xffff0000, v183
	v_lshlrev_b32_e32 v192, 16, v175
	v_and_b32_e32 v193, 0xffff0000, v175
	v_max_f32_e32 v250, 0x0da24260, v250
	v_max_f32_e32 v251, 0x0da24260, v251
	v_rcp_f32_e32 v250, v250
	v_rcp_f32_e32 v251, v251
	v_max_f32_e32 v192, 0x0da24260, v192
	v_max_f32_e32 v193, 0x0da24260, v193
	v_mul_f32_e32 v250, v250, v192
	v_mul_f32_e32 v251, v251, v193
	v_mul_f32_e32 v92, v92, v250
	v_mul_f32_e32 v93, v93, v251
	global_load_dwordx4 v[172:175], v248, s[70:71] offset:256
	global_load_dwordx4 v[180:183], v248, s[70:71] offset:2304
	s_waitcnt vmcnt(20)
	v_lshlrev_b32_e32 v250, 16, v188
	v_and_b32_e32 v251, 0xffff0000, v188
	v_lshlrev_b32_e32 v192, 16, v184
	v_and_b32_e32 v193, 0xffff0000, v184
	v_max_f32_e32 v250, 0x0da24260, v250
	v_max_f32_e32 v251, 0x0da24260, v251
	v_rcp_f32_e32 v250, v250
	v_rcp_f32_e32 v251, v251
	v_max_f32_e32 v192, 0x0da24260, v192
	v_max_f32_e32 v193, 0x0da24260, v193
	v_mul_f32_e32 v250, v250, v192
	v_mul_f32_e32 v251, v251, v193
	v_mul_f32_e32 v82, v82, v250
	v_mul_f32_e32 v83, v83, v251
	v_lshlrev_b32_e32 v250, 16, v189
	v_and_b32_e32 v251, 0xffff0000, v189
	v_lshlrev_b32_e32 v192, 16, v185
	v_and_b32_e32 v193, 0xffff0000, v185
	v_max_f32_e32 v250, 0x0da24260, v250
	v_max_f32_e32 v251, 0x0da24260, v251
	v_rcp_f32_e32 v250, v250
	v_rcp_f32_e32 v251, v251
	v_max_f32_e32 v192, 0x0da24260, v192
	v_max_f32_e32 v193, 0x0da24260, v193
	v_mul_f32_e32 v250, v250, v192
	v_mul_f32_e32 v251, v251, v193
	v_mul_f32_e32 v84, v84, v250
	v_mul_f32_e32 v85, v85, v251
	v_lshlrev_b32_e32 v250, 16, v190
	v_and_b32_e32 v251, 0xffff0000, v190
	v_lshlrev_b32_e32 v192, 16, v186
	v_and_b32_e32 v193, 0xffff0000, v186
	v_max_f32_e32 v250, 0x0da24260, v250
	v_max_f32_e32 v251, 0x0da24260, v251
	v_rcp_f32_e32 v250, v250
	v_rcp_f32_e32 v251, v251
	v_max_f32_e32 v192, 0x0da24260, v192
	v_max_f32_e32 v193, 0x0da24260, v193
	v_mul_f32_e32 v250, v250, v192
	v_mul_f32_e32 v251, v251, v193
	v_mul_f32_e32 v74, v74, v250
	v_mul_f32_e32 v75, v75, v251
	v_lshlrev_b32_e32 v250, 16, v191
	v_and_b32_e32 v251, 0xffff0000, v191
	v_lshlrev_b32_e32 v192, 16, v187
	v_and_b32_e32 v193, 0xffff0000, v187
	v_max_f32_e32 v250, 0x0da24260, v250
	v_max_f32_e32 v251, 0x0da24260, v251
	v_rcp_f32_e32 v250, v250
	v_rcp_f32_e32 v251, v251
	v_max_f32_e32 v192, 0x0da24260, v192
	v_max_f32_e32 v193, 0x0da24260, v193
	v_mul_f32_e32 v250, v250, v192
	v_mul_f32_e32 v251, v251, v193
	v_mul_f32_e32 v76, v76, v250
	v_mul_f32_e32 v77, v77, v251
	s_waitcnt vmcnt(18)
	v_lshlrev_b32_e32 v250, 16, v212
	v_and_b32_e32 v251, 0xffff0000, v212
	v_lshlrev_b32_e32 v192, 16, v198
	v_and_b32_e32 v193, 0xffff0000, v198
	v_max_f32_e32 v250, 0x0da24260, v250
	v_max_f32_e32 v251, 0x0da24260, v251
	v_rcp_f32_e32 v250, v250
	v_rcp_f32_e32 v251, v251
	v_max_f32_e32 v192, 0x0da24260, v192
	v_max_f32_e32 v193, 0x0da24260, v193
	v_mul_f32_e32 v250, v250, v192
	v_mul_f32_e32 v251, v251, v193
	v_mul_f32_e32 v86, v86, v250
	v_mul_f32_e32 v87, v87, v251
	v_lshlrev_b32_e32 v250, 16, v213
	v_and_b32_e32 v251, 0xffff0000, v213
	v_lshlrev_b32_e32 v192, 16, v199
	v_and_b32_e32 v193, 0xffff0000, v199
	v_max_f32_e32 v250, 0x0da24260, v250
	v_max_f32_e32 v251, 0x0da24260, v251
	v_rcp_f32_e32 v250, v250
	v_rcp_f32_e32 v251, v251
	v_max_f32_e32 v192, 0x0da24260, v192
	v_max_f32_e32 v193, 0x0da24260, v193
	v_mul_f32_e32 v250, v250, v192
	v_mul_f32_e32 v251, v251, v193
	v_mul_f32_e32 v88, v88, v250
	v_mul_f32_e32 v89, v89, v251
	v_lshlrev_b32_e32 v250, 16, v214
	v_and_b32_e32 v251, 0xffff0000, v214
	v_lshlrev_b32_e32 v192, 16, v200
	v_and_b32_e32 v193, 0xffff0000, v200
	v_max_f32_e32 v250, 0x0da24260, v250
	v_max_f32_e32 v251, 0x0da24260, v251
	v_rcp_f32_e32 v250, v250
	v_rcp_f32_e32 v251, v251
	v_max_f32_e32 v192, 0x0da24260, v192
	v_max_f32_e32 v193, 0x0da24260, v193
	v_mul_f32_e32 v250, v250, v192
	v_mul_f32_e32 v251, v251, v193
	v_mul_f32_e32 v78, v78, v250
	v_mul_f32_e32 v79, v79, v251
	v_lshlrev_b32_e32 v250, 16, v215
	v_and_b32_e32 v251, 0xffff0000, v215
	v_lshlrev_b32_e32 v192, 16, v201
	v_and_b32_e32 v193, 0xffff0000, v201
	v_max_f32_e32 v250, 0x0da24260, v250
	v_max_f32_e32 v251, 0x0da24260, v251
	v_rcp_f32_e32 v250, v250
	v_rcp_f32_e32 v251, v251
	v_max_f32_e32 v192, 0x0da24260, v192
	v_max_f32_e32 v193, 0x0da24260, v193
	v_mul_f32_e32 v250, v250, v192
	v_mul_f32_e32 v251, v251, v193
	v_mul_f32_e32 v80, v80, v250
	v_mul_f32_e32 v81, v81, v251
	s_waitcnt vmcnt(16)
	v_lshlrev_b32_e32 v250, 16, v220
	v_and_b32_e32 v251, 0xffff0000, v220
	v_lshlrev_b32_e32 v192, 16, v216
	v_and_b32_e32 v193, 0xffff0000, v216
	v_max_f32_e32 v250, 0x0da24260, v250
	v_max_f32_e32 v251, 0x0da24260, v251
	v_rcp_f32_e32 v250, v250
	v_rcp_f32_e32 v251, v251
	v_max_f32_e32 v192, 0x0da24260, v192
	v_max_f32_e32 v193, 0x0da24260, v193
	v_mul_f32_e32 v250, v250, v192
	v_mul_f32_e32 v251, v251, v193
	v_mul_f32_e32 v70, v70, v250
	v_mul_f32_e32 v71, v71, v251
	v_lshlrev_b32_e32 v250, 16, v221
	v_and_b32_e32 v251, 0xffff0000, v221
	v_lshlrev_b32_e32 v192, 16, v217
	v_and_b32_e32 v193, 0xffff0000, v217
	v_max_f32_e32 v250, 0x0da24260, v250
	v_max_f32_e32 v251, 0x0da24260, v251
	v_rcp_f32_e32 v250, v250
	v_rcp_f32_e32 v251, v251
	v_max_f32_e32 v192, 0x0da24260, v192
	v_max_f32_e32 v193, 0x0da24260, v193
	v_mul_f32_e32 v250, v250, v192
	v_mul_f32_e32 v251, v251, v193
	v_mul_f32_e32 v72, v72, v250
	v_mul_f32_e32 v73, v73, v251
	v_lshlrev_b32_e32 v250, 16, v222
	v_and_b32_e32 v251, 0xffff0000, v222
	v_lshlrev_b32_e32 v192, 16, v218
	v_and_b32_e32 v193, 0xffff0000, v218
	v_max_f32_e32 v250, 0x0da24260, v250
	v_max_f32_e32 v251, 0x0da24260, v251
	v_rcp_f32_e32 v250, v250
	v_rcp_f32_e32 v251, v251
	v_max_f32_e32 v192, 0x0da24260, v192
	v_max_f32_e32 v193, 0x0da24260, v193
	v_mul_f32_e32 v250, v250, v192
	v_mul_f32_e32 v251, v251, v193
	v_mul_f32_e32 v66, v66, v250
	v_mul_f32_e32 v67, v67, v251
	v_lshlrev_b32_e32 v250, 16, v223
	v_and_b32_e32 v251, 0xffff0000, v223
	v_lshlrev_b32_e32 v192, 16, v219
	v_and_b32_e32 v193, 0xffff0000, v219
	v_max_f32_e32 v250, 0x0da24260, v250
	v_max_f32_e32 v251, 0x0da24260, v251
	v_rcp_f32_e32 v250, v250
	v_rcp_f32_e32 v251, v251
	v_max_f32_e32 v192, 0x0da24260, v192
	v_max_f32_e32 v193, 0x0da24260, v193
	v_mul_f32_e32 v250, v250, v192
	v_mul_f32_e32 v251, v251, v193
	v_mul_f32_e32 v68, v68, v250
	v_mul_f32_e32 v69, v69, v251
	s_waitcnt vmcnt(14)
	v_lshlrev_b32_e32 v250, 16, v228
	v_and_b32_e32 v251, 0xffff0000, v228
	v_lshlrev_b32_e32 v192, 16, v224
	v_and_b32_e32 v193, 0xffff0000, v224
	v_max_f32_e32 v250, 0x0da24260, v250
	v_max_f32_e32 v251, 0x0da24260, v251
	v_rcp_f32_e32 v250, v250
	v_rcp_f32_e32 v251, v251
	v_max_f32_e32 v192, 0x0da24260, v192
	v_max_f32_e32 v193, 0x0da24260, v193
	v_mul_f32_e32 v250, v250, v192
	v_mul_f32_e32 v251, v251, v193
	v_mul_f32_e32 v62, v62, v250
	v_mul_f32_e32 v63, v63, v251
	v_lshlrev_b32_e32 v250, 16, v229
	v_and_b32_e32 v251, 0xffff0000, v229
	v_lshlrev_b32_e32 v192, 16, v225
	v_and_b32_e32 v193, 0xffff0000, v225
	v_max_f32_e32 v250, 0x0da24260, v250
	v_max_f32_e32 v251, 0x0da24260, v251
	v_rcp_f32_e32 v250, v250
	v_rcp_f32_e32 v251, v251
	v_max_f32_e32 v192, 0x0da24260, v192
	v_max_f32_e32 v193, 0x0da24260, v193
	v_mul_f32_e32 v250, v250, v192
	v_mul_f32_e32 v251, v251, v193
	v_mul_f32_e32 v64, v64, v250
	v_mul_f32_e32 v65, v65, v251
	v_lshlrev_b32_e32 v250, 16, v230
	v_and_b32_e32 v251, 0xffff0000, v230
	v_lshlrev_b32_e32 v192, 16, v226
	v_and_b32_e32 v193, 0xffff0000, v226
	v_max_f32_e32 v250, 0x0da24260, v250
	v_max_f32_e32 v251, 0x0da24260, v251
	v_rcp_f32_e32 v250, v250
	v_rcp_f32_e32 v251, v251
	v_max_f32_e32 v192, 0x0da24260, v192
	v_max_f32_e32 v193, 0x0da24260, v193
	v_mul_f32_e32 v250, v250, v192
	v_mul_f32_e32 v251, v251, v193
	v_mul_f32_e32 v58, v58, v250
	v_mul_f32_e32 v59, v59, v251
	v_lshlrev_b32_e32 v250, 16, v231
	v_and_b32_e32 v251, 0xffff0000, v231
	v_lshlrev_b32_e32 v192, 16, v227
	v_and_b32_e32 v193, 0xffff0000, v227
	v_max_f32_e32 v250, 0x0da24260, v250
	v_max_f32_e32 v251, 0x0da24260, v251
	v_rcp_f32_e32 v250, v250
	v_rcp_f32_e32 v251, v251
	v_max_f32_e32 v192, 0x0da24260, v192
	v_max_f32_e32 v193, 0x0da24260, v193
	v_mul_f32_e32 v250, v250, v192
	v_mul_f32_e32 v251, v251, v193
	v_mul_f32_e32 v60, v60, v250
	v_mul_f32_e32 v61, v61, v251
	s_waitcnt vmcnt(12)
	v_lshlrev_b32_e32 v250, 16, v236
	v_and_b32_e32 v251, 0xffff0000, v236
	v_lshlrev_b32_e32 v192, 16, v232
	v_and_b32_e32 v193, 0xffff0000, v232
	v_max_f32_e32 v250, 0x0da24260, v250
	v_max_f32_e32 v251, 0x0da24260, v251
	v_rcp_f32_e32 v250, v250
	v_rcp_f32_e32 v251, v251
	v_max_f32_e32 v192, 0x0da24260, v192
	v_max_f32_e32 v193, 0x0da24260, v193
	v_mul_f32_e32 v250, v250, v192
	v_mul_f32_e32 v251, v251, v193
	v_mul_f32_e32 v50, v50, v250
	v_mul_f32_e32 v51, v51, v251
	v_lshlrev_b32_e32 v250, 16, v237
	v_and_b32_e32 v251, 0xffff0000, v237
	v_lshlrev_b32_e32 v192, 16, v233
	v_and_b32_e32 v193, 0xffff0000, v233
	v_max_f32_e32 v250, 0x0da24260, v250
	v_max_f32_e32 v251, 0x0da24260, v251
	v_rcp_f32_e32 v250, v250
	v_rcp_f32_e32 v251, v251
	v_max_f32_e32 v192, 0x0da24260, v192
	v_max_f32_e32 v193, 0x0da24260, v193
	v_mul_f32_e32 v250, v250, v192
	v_mul_f32_e32 v251, v251, v193
	v_mul_f32_e32 v52, v52, v250
	v_mul_f32_e32 v53, v53, v251
	v_lshlrev_b32_e32 v250, 16, v238
	v_and_b32_e32 v251, 0xffff0000, v238
	v_lshlrev_b32_e32 v192, 16, v234
	v_and_b32_e32 v193, 0xffff0000, v234
	v_max_f32_e32 v250, 0x0da24260, v250
	v_max_f32_e32 v251, 0x0da24260, v251
	v_rcp_f32_e32 v250, v250
	v_rcp_f32_e32 v251, v251
	v_max_f32_e32 v192, 0x0da24260, v192
	v_max_f32_e32 v193, 0x0da24260, v193
	v_mul_f32_e32 v250, v250, v192
	v_mul_f32_e32 v251, v251, v193
	v_mul_f32_e32 v42, v42, v250
	v_mul_f32_e32 v43, v43, v251
	v_lshlrev_b32_e32 v250, 16, v239
	v_and_b32_e32 v251, 0xffff0000, v239
	v_lshlrev_b32_e32 v192, 16, v235
	v_and_b32_e32 v193, 0xffff0000, v235
	v_max_f32_e32 v250, 0x0da24260, v250
	v_max_f32_e32 v251, 0x0da24260, v251
	v_rcp_f32_e32 v250, v250
	v_rcp_f32_e32 v251, v251
	v_max_f32_e32 v192, 0x0da24260, v192
	v_max_f32_e32 v193, 0x0da24260, v193
	v_mul_f32_e32 v250, v250, v192
	v_mul_f32_e32 v251, v251, v193
	v_mul_f32_e32 v44, v44, v250
	v_mul_f32_e32 v45, v45, v251
	s_waitcnt vmcnt(10)
	v_lshlrev_b32_e32 v250, 16, v244
	v_and_b32_e32 v251, 0xffff0000, v244
	v_lshlrev_b32_e32 v192, 16, v240
	v_and_b32_e32 v193, 0xffff0000, v240
	v_max_f32_e32 v250, 0x0da24260, v250
	v_max_f32_e32 v251, 0x0da24260, v251
	v_rcp_f32_e32 v250, v250
	v_rcp_f32_e32 v251, v251
	v_max_f32_e32 v192, 0x0da24260, v192
	v_max_f32_e32 v193, 0x0da24260, v193
	v_mul_f32_e32 v250, v250, v192
	v_mul_f32_e32 v251, v251, v193
	v_mul_f32_e32 v54, v54, v250
	v_mul_f32_e32 v55, v55, v251
	v_lshlrev_b32_e32 v250, 16, v245
	v_and_b32_e32 v251, 0xffff0000, v245
	v_lshlrev_b32_e32 v192, 16, v241
	v_and_b32_e32 v193, 0xffff0000, v241
	v_max_f32_e32 v250, 0x0da24260, v250
	v_max_f32_e32 v251, 0x0da24260, v251
	v_rcp_f32_e32 v250, v250
	v_rcp_f32_e32 v251, v251
	v_max_f32_e32 v192, 0x0da24260, v192
	v_max_f32_e32 v193, 0x0da24260, v193
	v_mul_f32_e32 v250, v250, v192
	v_mul_f32_e32 v251, v251, v193
	v_mul_f32_e32 v56, v56, v250
	v_mul_f32_e32 v57, v57, v251
	v_lshlrev_b32_e32 v250, 16, v246
	v_and_b32_e32 v251, 0xffff0000, v246
	v_lshlrev_b32_e32 v192, 16, v242
	v_and_b32_e32 v193, 0xffff0000, v242
	v_max_f32_e32 v250, 0x0da24260, v250
	v_max_f32_e32 v251, 0x0da24260, v251
	v_rcp_f32_e32 v250, v250
	v_rcp_f32_e32 v251, v251
	v_max_f32_e32 v192, 0x0da24260, v192
	v_max_f32_e32 v193, 0x0da24260, v193
	v_mul_f32_e32 v250, v250, v192
	v_mul_f32_e32 v251, v251, v193
	v_mul_f32_e32 v46, v46, v250
	v_mul_f32_e32 v47, v47, v251
	v_lshlrev_b32_e32 v250, 16, v247
	v_and_b32_e32 v251, 0xffff0000, v247
	v_lshlrev_b32_e32 v192, 16, v243
	v_and_b32_e32 v193, 0xffff0000, v243
	v_max_f32_e32 v250, 0x0da24260, v250
	v_max_f32_e32 v251, 0x0da24260, v251
	v_rcp_f32_e32 v250, v250
	v_rcp_f32_e32 v251, v251
	v_max_f32_e32 v192, 0x0da24260, v192
	v_max_f32_e32 v193, 0x0da24260, v193
	v_mul_f32_e32 v250, v250, v192
	v_mul_f32_e32 v251, v251, v193
	v_mul_f32_e32 v48, v48, v250
	v_mul_f32_e32 v49, v49, v251
	s_waitcnt vmcnt(8)
	v_lshlrev_b32_e32 v250, 16, v134
	v_and_b32_e32 v251, 0xffff0000, v134
	v_lshlrev_b32_e32 v192, 16, v130
	v_and_b32_e32 v193, 0xffff0000, v130
	v_max_f32_e32 v250, 0x0da24260, v250
	v_max_f32_e32 v251, 0x0da24260, v251
	v_rcp_f32_e32 v250, v250
	v_rcp_f32_e32 v251, v251
	v_max_f32_e32 v192, 0x0da24260, v192
	v_max_f32_e32 v193, 0x0da24260, v193
	v_mul_f32_e32 v250, v250, v192
	v_mul_f32_e32 v251, v251, v193
	v_mul_f32_e32 v38, v38, v250
	v_mul_f32_e32 v39, v39, v251
	v_lshlrev_b32_e32 v250, 16, v135
	v_and_b32_e32 v251, 0xffff0000, v135
	v_lshlrev_b32_e32 v192, 16, v131
	v_and_b32_e32 v193, 0xffff0000, v131
	v_max_f32_e32 v250, 0x0da24260, v250
	v_max_f32_e32 v251, 0x0da24260, v251
	v_rcp_f32_e32 v250, v250
	v_rcp_f32_e32 v251, v251
	v_max_f32_e32 v192, 0x0da24260, v192
	v_max_f32_e32 v193, 0x0da24260, v193
	v_mul_f32_e32 v250, v250, v192
	v_mul_f32_e32 v251, v251, v193
	v_mul_f32_e32 v40, v40, v250
	v_mul_f32_e32 v41, v41, v251
	v_lshlrev_b32_e32 v250, 16, v136
	v_and_b32_e32 v251, 0xffff0000, v136
	v_lshlrev_b32_e32 v192, 16, v132
	v_and_b32_e32 v193, 0xffff0000, v132
	v_max_f32_e32 v250, 0x0da24260, v250
	v_max_f32_e32 v251, 0x0da24260, v251
	v_rcp_f32_e32 v250, v250
	v_rcp_f32_e32 v251, v251
	v_max_f32_e32 v192, 0x0da24260, v192
	v_max_f32_e32 v193, 0x0da24260, v193
	v_mul_f32_e32 v250, v250, v192
	v_mul_f32_e32 v251, v251, v193
	v_mul_f32_e32 v34, v34, v250
	v_mul_f32_e32 v35, v35, v251
	v_lshlrev_b32_e32 v250, 16, v137
	v_and_b32_e32 v251, 0xffff0000, v137
	v_lshlrev_b32_e32 v192, 16, v133
	v_and_b32_e32 v193, 0xffff0000, v133
	v_max_f32_e32 v250, 0x0da24260, v250
	v_max_f32_e32 v251, 0x0da24260, v251
	v_rcp_f32_e32 v250, v250
	v_rcp_f32_e32 v251, v251
	v_max_f32_e32 v192, 0x0da24260, v192
	v_max_f32_e32 v193, 0x0da24260, v193
	v_mul_f32_e32 v250, v250, v192
	v_mul_f32_e32 v251, v251, v193
	v_mul_f32_e32 v36, v36, v250
	v_mul_f32_e32 v37, v37, v251
	s_waitcnt vmcnt(6)
	v_lshlrev_b32_e32 v250, 16, v142
	v_and_b32_e32 v251, 0xffff0000, v142
	v_lshlrev_b32_e32 v192, 16, v138
	v_and_b32_e32 v193, 0xffff0000, v138
	v_max_f32_e32 v250, 0x0da24260, v250
	v_max_f32_e32 v251, 0x0da24260, v251
	v_rcp_f32_e32 v250, v250
	v_rcp_f32_e32 v251, v251
	v_max_f32_e32 v192, 0x0da24260, v192
	v_max_f32_e32 v193, 0x0da24260, v193
	v_mul_f32_e32 v250, v250, v192
	v_mul_f32_e32 v251, v251, v193
	v_mul_f32_e32 v30, v30, v250
	v_mul_f32_e32 v31, v31, v251
	v_lshlrev_b32_e32 v250, 16, v143
	v_and_b32_e32 v251, 0xffff0000, v143
	v_lshlrev_b32_e32 v192, 16, v139
	v_and_b32_e32 v193, 0xffff0000, v139
	v_max_f32_e32 v250, 0x0da24260, v250
	v_max_f32_e32 v251, 0x0da24260, v251
	v_rcp_f32_e32 v250, v250
	v_rcp_f32_e32 v251, v251
	v_max_f32_e32 v192, 0x0da24260, v192
	v_max_f32_e32 v193, 0x0da24260, v193
	v_mul_f32_e32 v250, v250, v192
	v_mul_f32_e32 v251, v251, v193
	v_mul_f32_e32 v32, v32, v250
	v_mul_f32_e32 v33, v33, v251
	v_lshlrev_b32_e32 v250, 16, v144
	v_and_b32_e32 v251, 0xffff0000, v144
	v_lshlrev_b32_e32 v192, 16, v140
	v_and_b32_e32 v193, 0xffff0000, v140
	v_max_f32_e32 v250, 0x0da24260, v250
	v_max_f32_e32 v251, 0x0da24260, v251
	v_rcp_f32_e32 v250, v250
	v_rcp_f32_e32 v251, v251
	v_max_f32_e32 v192, 0x0da24260, v192
	v_max_f32_e32 v193, 0x0da24260, v193
	v_mul_f32_e32 v250, v250, v192
	v_mul_f32_e32 v251, v251, v193
	v_mul_f32_e32 v26, v26, v250
	v_mul_f32_e32 v27, v27, v251
	v_lshlrev_b32_e32 v250, 16, v145
	v_and_b32_e32 v251, 0xffff0000, v145
	v_lshlrev_b32_e32 v192, 16, v141
	v_and_b32_e32 v193, 0xffff0000, v141
	v_max_f32_e32 v250, 0x0da24260, v250
	v_max_f32_e32 v251, 0x0da24260, v251
	v_rcp_f32_e32 v250, v250
	v_rcp_f32_e32 v251, v251
	v_max_f32_e32 v192, 0x0da24260, v192
	v_max_f32_e32 v193, 0x0da24260, v193
	v_mul_f32_e32 v250, v250, v192
	v_mul_f32_e32 v251, v251, v193
	v_mul_f32_e32 v28, v28, v250
	v_mul_f32_e32 v29, v29, v251
	s_waitcnt vmcnt(4)
	v_lshlrev_b32_e32 v250, 16, v150
	v_and_b32_e32 v251, 0xffff0000, v150
	v_lshlrev_b32_e32 v192, 16, v146
	v_and_b32_e32 v193, 0xffff0000, v146
	v_max_f32_e32 v250, 0x0da24260, v250
	v_max_f32_e32 v251, 0x0da24260, v251
	v_rcp_f32_e32 v250, v250
	v_rcp_f32_e32 v251, v251
	v_max_f32_e32 v192, 0x0da24260, v192
	v_max_f32_e32 v193, 0x0da24260, v193
	v_mul_f32_e32 v250, v250, v192
	v_mul_f32_e32 v251, v251, v193
	v_mul_f32_e32 v18, v18, v250
	v_mul_f32_e32 v19, v19, v251
	v_lshlrev_b32_e32 v250, 16, v151
	v_and_b32_e32 v251, 0xffff0000, v151
	v_lshlrev_b32_e32 v192, 16, v147
	v_and_b32_e32 v193, 0xffff0000, v147
	v_max_f32_e32 v250, 0x0da24260, v250
	v_max_f32_e32 v251, 0x0da24260, v251
	v_rcp_f32_e32 v250, v250
	v_rcp_f32_e32 v251, v251
	v_max_f32_e32 v192, 0x0da24260, v192
	v_max_f32_e32 v193, 0x0da24260, v193
	v_mul_f32_e32 v250, v250, v192
	v_mul_f32_e32 v251, v251, v193
	v_mul_f32_e32 v20, v20, v250
	v_mul_f32_e32 v21, v21, v251
	v_lshlrev_b32_e32 v250, 16, v152
	v_and_b32_e32 v251, 0xffff0000, v152
	v_lshlrev_b32_e32 v192, 16, v148
	v_and_b32_e32 v193, 0xffff0000, v148
	v_max_f32_e32 v250, 0x0da24260, v250
	v_max_f32_e32 v251, 0x0da24260, v251
	v_rcp_f32_e32 v250, v250
	v_rcp_f32_e32 v251, v251
	v_max_f32_e32 v192, 0x0da24260, v192
	v_max_f32_e32 v193, 0x0da24260, v193
	v_mul_f32_e32 v250, v250, v192
	v_mul_f32_e32 v251, v251, v193
	v_mul_f32_e32 v10, v10, v250
	v_mul_f32_e32 v11, v11, v251
	v_lshlrev_b32_e32 v250, 16, v153
	v_and_b32_e32 v251, 0xffff0000, v153
	v_lshlrev_b32_e32 v192, 16, v149
	v_and_b32_e32 v193, 0xffff0000, v149
	v_max_f32_e32 v250, 0x0da24260, v250
	v_max_f32_e32 v251, 0x0da24260, v251
	v_rcp_f32_e32 v250, v250
	v_rcp_f32_e32 v251, v251
	v_max_f32_e32 v192, 0x0da24260, v192
	v_max_f32_e32 v193, 0x0da24260, v193
	v_mul_f32_e32 v250, v250, v192
	v_mul_f32_e32 v251, v251, v193
	v_mul_f32_e32 v12, v12, v250
	v_mul_f32_e32 v13, v13, v251
	s_waitcnt vmcnt(2)
	v_lshlrev_b32_e32 v250, 16, v168
	v_and_b32_e32 v251, 0xffff0000, v168
	v_lshlrev_b32_e32 v192, 16, v164
	v_and_b32_e32 v193, 0xffff0000, v164
	v_max_f32_e32 v250, 0x0da24260, v250
	v_max_f32_e32 v251, 0x0da24260, v251
	v_rcp_f32_e32 v250, v250
	v_rcp_f32_e32 v251, v251
	v_max_f32_e32 v192, 0x0da24260, v192
	v_max_f32_e32 v193, 0x0da24260, v193
	v_mul_f32_e32 v250, v250, v192
	v_mul_f32_e32 v251, v251, v193
	v_mul_f32_e32 v22, v22, v250
	v_mul_f32_e32 v23, v23, v251
	v_lshlrev_b32_e32 v250, 16, v169
	v_and_b32_e32 v251, 0xffff0000, v169
	v_lshlrev_b32_e32 v192, 16, v165
	v_and_b32_e32 v193, 0xffff0000, v165
	v_max_f32_e32 v250, 0x0da24260, v250
	v_max_f32_e32 v251, 0x0da24260, v251
	v_rcp_f32_e32 v250, v250
	v_rcp_f32_e32 v251, v251
	v_max_f32_e32 v192, 0x0da24260, v192
	v_max_f32_e32 v193, 0x0da24260, v193
	v_mul_f32_e32 v250, v250, v192
	v_mul_f32_e32 v251, v251, v193
	v_mul_f32_e32 v24, v24, v250
	v_mul_f32_e32 v25, v25, v251
	v_lshlrev_b32_e32 v250, 16, v170
	v_and_b32_e32 v251, 0xffff0000, v170
	v_lshlrev_b32_e32 v192, 16, v166
	v_and_b32_e32 v193, 0xffff0000, v166
	v_max_f32_e32 v250, 0x0da24260, v250
	v_max_f32_e32 v251, 0x0da24260, v251
	v_rcp_f32_e32 v250, v250
	v_rcp_f32_e32 v251, v251
	v_max_f32_e32 v192, 0x0da24260, v192
	v_max_f32_e32 v193, 0x0da24260, v193
	v_mul_f32_e32 v250, v250, v192
	v_mul_f32_e32 v251, v251, v193
	v_mul_f32_e32 v14, v14, v250
	v_mul_f32_e32 v15, v15, v251
	v_lshlrev_b32_e32 v250, 16, v171
	v_and_b32_e32 v251, 0xffff0000, v171
	v_lshlrev_b32_e32 v192, 16, v167
	v_and_b32_e32 v193, 0xffff0000, v167
	v_max_f32_e32 v250, 0x0da24260, v250
	v_max_f32_e32 v251, 0x0da24260, v251
	v_rcp_f32_e32 v250, v250
	v_rcp_f32_e32 v251, v251
	v_max_f32_e32 v192, 0x0da24260, v192
	v_max_f32_e32 v193, 0x0da24260, v193
	v_mul_f32_e32 v250, v250, v192
	v_mul_f32_e32 v251, v251, v193
	v_mul_f32_e32 v16, v16, v250
	v_mul_f32_e32 v17, v17, v251
	s_waitcnt vmcnt(0)
	v_lshlrev_b32_e32 v250, 16, v180
	v_and_b32_e32 v251, 0xffff0000, v180
	v_lshlrev_b32_e32 v192, 16, v172
	v_and_b32_e32 v193, 0xffff0000, v172
	v_max_f32_e32 v250, 0x0da24260, v250
	v_max_f32_e32 v251, 0x0da24260, v251
	v_rcp_f32_e32 v250, v250
	v_rcp_f32_e32 v251, v251
	v_max_f32_e32 v192, 0x0da24260, v192
	v_max_f32_e32 v193, 0x0da24260, v193
	v_mul_f32_e32 v250, v250, v192
	v_mul_f32_e32 v251, v251, v193
	v_mul_f32_e32 v6, v6, v250
	v_mul_f32_e32 v7, v7, v251
	v_lshlrev_b32_e32 v250, 16, v181
	v_and_b32_e32 v251, 0xffff0000, v181
	v_lshlrev_b32_e32 v192, 16, v173
	v_and_b32_e32 v193, 0xffff0000, v173
	v_max_f32_e32 v250, 0x0da24260, v250
	v_max_f32_e32 v251, 0x0da24260, v251
	v_rcp_f32_e32 v250, v250
	v_rcp_f32_e32 v251, v251
	v_max_f32_e32 v192, 0x0da24260, v192
	v_max_f32_e32 v193, 0x0da24260, v193
	v_mul_f32_e32 v250, v250, v192
	v_mul_f32_e32 v251, v251, v193
	v_mul_f32_e32 v8, v8, v250
	v_mul_f32_e32 v9, v9, v251
	v_lshlrev_b32_e32 v250, 16, v182
	v_and_b32_e32 v251, 0xffff0000, v182
	v_lshlrev_b32_e32 v192, 16, v174
	v_and_b32_e32 v193, 0xffff0000, v174
	v_max_f32_e32 v250, 0x0da24260, v250
	v_max_f32_e32 v251, 0x0da24260, v251
	v_rcp_f32_e32 v250, v250
	v_rcp_f32_e32 v251, v251
	v_max_f32_e32 v192, 0x0da24260, v192
	v_max_f32_e32 v193, 0x0da24260, v193
	v_mul_f32_e32 v250, v250, v192
	v_mul_f32_e32 v251, v251, v193
	v_mul_f32_e32 v2, v2, v250
	v_mul_f32_e32 v3, v3, v251
	v_lshlrev_b32_e32 v250, 16, v183
	v_and_b32_e32 v251, 0xffff0000, v183
	v_lshlrev_b32_e32 v192, 16, v175
	v_and_b32_e32 v193, 0xffff0000, v175
	v_max_f32_e32 v250, 0x0da24260, v250
	v_max_f32_e32 v251, 0x0da24260, v251
	v_rcp_f32_e32 v250, v250
	v_rcp_f32_e32 v251, v251
	v_max_f32_e32 v192, 0x0da24260, v192
	v_max_f32_e32 v193, 0x0da24260, v193
	v_mul_f32_e32 v250, v250, v192
	v_mul_f32_e32 v251, v251, v193
	v_mul_f32_e32 v4, v4, v250
	v_mul_f32_e32 v5, v5, v251
	s_cmp_lg_u32 s45, 0
	s_cbranch_scc1 .Lm_done
	v_readlane_b32 s2, v253, 7
	s_cmp_lg_u32 s2, 0
	s_cbranch_scc1 .Lsw_bar
	v_readlane_b32 s2, v253, 1
	v_readlane_b32 s3, v253, 2
	s_load_dwordx2 s[2:3], s[2:3], 0xd8
	v_readlane_b32 s0, v255, 53
	v_mov_b32_e32 v250, 0
	s_mov_b32 s1, 0
	s_waitcnt lgkmcnt(0)
	s_add_u32 s2, s2, 0x3500
	s_addc_u32 s3, s3, 0
.Lsw_poll:
	global_load_dword v251, v250, s[2:3] sc1
	s_waitcnt vmcnt(0)
	v_cmp_ne_u32_e32 vcc, s0, v251
	s_cbranch_vccnz .Lsw_got
	s_sleep 1
	s_add_i32 s1, s1, 1
	s_cmp_lt_u32 s1, 0x800
	s_cbranch_scc1 .Lsw_poll
.Lsw_got:
	buffer_inv sc1
	s_waitcnt vmcnt(0)
.Lsw_bar:
	s_barrier
	s_branch .Lm_done
